# same as previous + barrier poll bound raised 8x (robustness only)
# speedup vs baseline: 1.0039x; 1.0039x over previous
.Lgb_spin_1:
	global_load_dword v3, v2, s[6:7] sc1
	s_waitcnt vmcnt(0)
	v_readfirstlane_b32 s11, v3
	s_lshr_b32 s11, s11, 16
	s_cmp_lg_u32 s11, s8
	s_cbranch_scc1 .Lgb_done_1
	s_sleep 1
	s_add_i32 s10, s10, 1
	s_cmp_lt_u32 s10, 0x40000
	s_cbranch_scc1 .Lgb_spin_1
